# Dn split-K fixup: the 4-iteration partial-sum loops unrolled so all 16 slab loads of a (b,n) pair are in flight together (same summation order), on top of v12
# speedup vs baseline: 1.0143x; 1.0083x over previous
; template <class Epi> DI void gemm_fixup(int N, int K, const Epi& E, const float* part, int tid) {
;     ...
;         for (int b = 0; b < 2; ++b)
; #pragma unroll
;             for (int n = 0; n < 2; ++n) { const f32x4* pp = (const f32x4*)part + ((size_t)(j * S.S) * 32 + (((ai * 2 + b) * 4 + m) * 2 + n)) * 512 + tid;
;                 f32x4 v0 = {0.f, 0.f, 0.f, 0.f}, v1 = v0, v2 = v0, v3 = v0;
;                 for (int sl = 0; sl + 3 < S.S; sl += 4) { v0 += pp[(size_t)sl * 16384]; v1 += pp[(size_t)(sl + 1) * 16384]; v2 += pp[(size_t)(sl + 2) * 16384]; v3 += pp[(size_t)(sl + 3) * 16384]; }
;                 for (int sl = S.S & ~3; sl < S.S; ++sl) v0 += pp[(size_t)sl * 16384];
;                 a4[b][n] = (v0 + v1) + (v2 + v3); }
.LBB0_1727:
	s_and_b32 s8, s16, 3
	s_lshl_b32 s9, s17, 15
	s_and_b32 s9, s9, 0x20000
	s_lshl_b32 s8, s8, 14
	s_or_b32 s19, s9, s8
	s_mul_i32 s8, s25, s2
	s_ashr_i32 s9, s8, 31
	s_and_b64 vcc, exec, s[6:7]
	s_lshl_b64 s[26:27], s[8:9], 18
	s_cbranch_vccnz .LBB0_1730
	s_add_u32 s8, s26, s19
	s_addc_u32 s9, s27, 0
	v_mov_b32_e32 v38, 0
	v_lshl_add_u64 v[2:3], v[20:21], 0, s[8:9]
	s_mov_b32 s8, 3
	v_mov_b32_e32 v39, v38
	v_mov_b32_e32 v40, v38
	v_mov_b32_e32 v41, v38
	v_mov_b32_e32 v44, v38
	v_mov_b32_e32 v45, v38
	v_mov_b32_e32 v42, v38
	v_mov_b32_e32 v43, v38
	v_mov_b32_e32 v46, v38
	v_mov_b32_e32 v47, v38
	v_mov_b32_e32 v48, v38
	v_mov_b32_e32 v49, v38
	s_waitcnt lgkmcnt(0)
	v_mov_b32_e32 v4, v38
	v_mov_b32_e32 v5, v38
	v_mov_b32_e32 v6, v38
	v_mov_b32_e32 v7, v38
	s_cmp_eq_u32 s2, 16
	s_cbranch_scc0 .LBB0_1729
	v_add_co_u32_e32 v12, vcc, s4, v2
	global_load_dwordx4 v[8:11], v[2:3], off
	s_nop 0
	v_addc_co_u32_e32 v13, vcc, -1, v3, vcc
	v_add_co_u32_e32 v16, vcc, s5, v2
	s_nop 0
	s_nop 0
	v_addc_co_u32_e32 v17, vcc, -1, v3, vcc
	v_add_co_u32_e32 v50, vcc, s11, v2
	s_nop 0
	s_nop 0
	v_addc_co_u32_e32 v51, vcc, 0, v3, vcc
	global_load_dwordx4 v[12:15], v[12:13], off
	s_nop 0
	global_load_dwordx4 v[16:19], v[16:17], off
	s_nop 0
	global_load_dwordx4 v[50:53], v[50:51], off
	v_lshl_add_u64 v[2:3], v[2:3], 0, s[20:21]
	v_add_co_u32_e32 v188, vcc, s4, v2
	global_load_dwordx4 v[184:187], v[2:3], off
	s_nop 0
	v_addc_co_u32_e32 v189, vcc, -1, v3, vcc
	v_add_co_u32_e32 v192, vcc, s5, v2
	s_nop 0
	s_nop 0
	v_addc_co_u32_e32 v193, vcc, -1, v3, vcc
	v_add_co_u32_e32 v196, vcc, s11, v2
	s_nop 0
	s_nop 0
	v_addc_co_u32_e32 v197, vcc, 0, v3, vcc
	global_load_dwordx4 v[188:191], v[188:189], off
	s_nop 0
	global_load_dwordx4 v[192:195], v[192:193], off
	s_nop 0
	global_load_dwordx4 v[196:199], v[196:197], off
	v_lshl_add_u64 v[2:3], v[2:3], 0, s[20:21]
	v_add_co_u32_e32 v204, vcc, s4, v2
	global_load_dwordx4 v[200:203], v[2:3], off
	s_nop 0
	v_addc_co_u32_e32 v205, vcc, -1, v3, vcc
	v_add_co_u32_e32 v208, vcc, s5, v2
	s_nop 0
	s_nop 0
	v_addc_co_u32_e32 v209, vcc, -1, v3, vcc
	v_add_co_u32_e32 v212, vcc, s11, v2
	s_nop 0
	s_nop 0
	v_addc_co_u32_e32 v213, vcc, 0, v3, vcc
	global_load_dwordx4 v[204:207], v[204:205], off
	s_nop 0
	global_load_dwordx4 v[208:211], v[208:209], off
	s_nop 0
	global_load_dwordx4 v[212:215], v[212:213], off
	v_lshl_add_u64 v[2:3], v[2:3], 0, s[20:21]
	v_add_co_u32_e32 v220, vcc, s4, v2
	global_load_dwordx4 v[216:219], v[2:3], off
	s_nop 0
	v_addc_co_u32_e32 v221, vcc, -1, v3, vcc
	v_add_co_u32_e32 v224, vcc, s5, v2
	s_nop 0
	s_nop 0
	v_addc_co_u32_e32 v225, vcc, -1, v3, vcc
	v_add_co_u32_e32 v228, vcc, s11, v2
	s_nop 0
	s_nop 0
	v_addc_co_u32_e32 v229, vcc, 0, v3, vcc
	global_load_dwordx4 v[220:223], v[220:221], off
	s_nop 0
	global_load_dwordx4 v[224:227], v[224:225], off
	s_nop 0
	global_load_dwordx4 v[228:231], v[228:229], off
	v_lshl_add_u64 v[2:3], v[2:3], 0, s[20:21]
	s_waitcnt vmcnt(12)
	v_pk_add_f32 v[42:43], v[42:43], v[10:11]
	v_pk_add_f32 v[44:45], v[44:45], v[8:9]
	v_pk_add_f32 v[6:7], v[6:7], v[14:15]
	v_pk_add_f32 v[4:5], v[4:5], v[12:13]
	v_pk_add_f32 v[48:49], v[48:49], v[18:19]
	v_pk_add_f32 v[46:47], v[46:47], v[16:17]
	v_pk_add_f32 v[40:41], v[40:41], v[52:53]
	v_pk_add_f32 v[38:39], v[38:39], v[50:51]
	s_waitcnt vmcnt(8)
	v_pk_add_f32 v[42:43], v[42:43], v[186:187]
	v_pk_add_f32 v[44:45], v[44:45], v[184:185]
	v_pk_add_f32 v[6:7], v[6:7], v[190:191]
	v_pk_add_f32 v[4:5], v[4:5], v[188:189]
	v_pk_add_f32 v[48:49], v[48:49], v[194:195]
	v_pk_add_f32 v[46:47], v[46:47], v[192:193]
	v_pk_add_f32 v[40:41], v[40:41], v[198:199]
	v_pk_add_f32 v[38:39], v[38:39], v[196:197]
	s_waitcnt vmcnt(4)
	v_pk_add_f32 v[42:43], v[42:43], v[202:203]
	v_pk_add_f32 v[44:45], v[44:45], v[200:201]
	v_pk_add_f32 v[6:7], v[6:7], v[206:207]
	v_pk_add_f32 v[4:5], v[4:5], v[204:205]
	v_pk_add_f32 v[48:49], v[48:49], v[210:211]
	v_pk_add_f32 v[46:47], v[46:47], v[208:209]
	v_pk_add_f32 v[40:41], v[40:41], v[214:215]
	v_pk_add_f32 v[38:39], v[38:39], v[212:213]
	s_waitcnt vmcnt(0)
	v_pk_add_f32 v[42:43], v[42:43], v[218:219]
	v_pk_add_f32 v[44:45], v[44:45], v[216:217]
	v_pk_add_f32 v[6:7], v[6:7], v[222:223]
	v_pk_add_f32 v[4:5], v[4:5], v[220:221]
	v_pk_add_f32 v[48:49], v[48:49], v[226:227]
	v_pk_add_f32 v[46:47], v[46:47], v[224:225]
	v_pk_add_f32 v[40:41], v[40:41], v[230:231]
	v_pk_add_f32 v[38:39], v[38:39], v[228:229]
	s_branch .Lfx_after_7
.LBB0_1729:
	v_add_co_u32_e32 v12, vcc, s4, v2
	global_load_dwordx4 v[8:11], v[2:3], off
	s_nop 0
	v_addc_co_u32_e32 v13, vcc, -1, v3, vcc
	v_add_co_u32_e32 v16, vcc, s5, v2
	s_add_i32 s8, s8, 4
	s_nop 0
	v_addc_co_u32_e32 v17, vcc, -1, v3, vcc
	v_add_co_u32_e32 v50, vcc, s11, v2
	s_cmp_ge_i32 s8, s2
	s_nop 0
	v_addc_co_u32_e32 v51, vcc, 0, v3, vcc
	global_load_dwordx4 v[12:15], v[12:13], off
	s_nop 0
	global_load_dwordx4 v[16:19], v[16:17], off
	s_nop 0
	global_load_dwordx4 v[50:53], v[50:51], off
	v_lshl_add_u64 v[2:3], v[2:3], 0, s[20:21]
	s_waitcnt vmcnt(3)
	v_pk_add_f32 v[42:43], v[42:43], v[10:11]
	v_pk_add_f32 v[44:45], v[44:45], v[8:9]
	s_waitcnt vmcnt(2)
	v_pk_add_f32 v[6:7], v[6:7], v[14:15]
	v_pk_add_f32 v[4:5], v[4:5], v[12:13]
	s_waitcnt vmcnt(1)
	v_pk_add_f32 v[48:49], v[48:49], v[18:19]
	v_pk_add_f32 v[46:47], v[46:47], v[16:17]
	s_waitcnt vmcnt(0)
	v_pk_add_f32 v[40:41], v[40:41], v[52:53]
	v_pk_add_f32 v[38:39], v[38:39], v[50:51]
	s_cbranch_scc0 .LBB0_1729
.Lfx_after_7:
	s_branch .LBB0_1731
.LBB0_1730:
	v_mov_b32_e32 v2, v0
	v_mov_b32_e32 v3, v0
	v_mov_b32_e32 v1, v0
	v_mov_b32_e32 v41, 0
	s_waitcnt lgkmcnt(0)
	v_mov_b64_e32 v[6:7], v[2:3]
	v_mov_b32_e32 v40, v41
	v_mov_b32_e32 v39, v41
	v_mov_b32_e32 v38, v41
	v_mov_b32_e32 v43, v41
	v_mov_b32_e32 v42, v41
	v_mov_b32_e32 v45, v41
	v_mov_b32_e32 v44, v41
	v_mov_b32_e32 v49, v41
	v_mov_b32_e32 v48, v41
	v_mov_b32_e32 v47, v41
	v_mov_b32_e32 v46, v41
	v_mov_b64_e32 v[4:5], v[0:1]

; template <class Epi> DI void gemm_fixup(int N, int K, const Epi& E, const float* part, int tid) {
;     ...
;     for (int it = blockIdx.x; it < S.ntail * 8; it += gridDim.x) { const int j = it >> 3, ai = (it >> 2) & 1, m = it & 3; Unit u; S.map(S.nwhole * S.G + j, u);
;         f32x4 a4[2][2];
; #pragma unroll
;         for (int b = 0; b < 2; ++b)
; #pragma unroll
;             for (int n = 0; n < 2; ++n) { const f32x4* pp = (const f32x4*)part + ((size_t)(j * S.S) * 32 + (((ai * 2 + b) * 4 + m) * 2 + n)) * 512 + tid;
;                 f32x4 v0 = {0.f, 0.f, 0.f, 0.f}, v1 = v0, v2 = v0, v3 = v0;
;                 for (int sl = 0; sl + 3 < S.S; sl += 4) { v0 += pp[(size_t)sl * 16384]; v1 += pp[(size_t)(sl + 1) * 16384]; v2 += pp[(size_t)(sl + 2) * 16384]; v3 += pp[(size_t)(sl + 3) * 16384]; }
;                 for (int sl = S.S & ~3; sl < S.S; ++sl) v0 += pp[(size_t)sl * 16384];
;                 a4[b][n] = (v0 + v1) + (v2 + v3); }
.LBB0_1734:
	s_and_b64 vcc, exec, s[6:7]
	s_cbranch_vccnz .LBB0_1738
	s_add_u32 s34, s26, s19
	s_addc_u32 s35, s27, 0
	v_mov_b32_e32 v50, 0
	v_lshl_add_u64 v[2:3], v[24:25], 0, s[34:35]
	s_mov_b32 s29, 3
	v_mov_b32_e32 v51, v50
	v_mov_b32_e32 v52, v50
	v_mov_b32_e32 v53, v50
	v_mov_b32_e32 v56, v50
	v_mov_b32_e32 v57, v50
	v_mov_b32_e32 v54, v50
	v_mov_b32_e32 v55, v50
	v_mov_b32_e32 v58, v50
	v_mov_b32_e32 v59, v50
	v_mov_b32_e32 v60, v50
	v_mov_b32_e32 v61, v50
	v_mov_b32_e32 v8, v50
	v_mov_b32_e32 v9, v50
	v_mov_b32_e32 v10, v50
	v_mov_b32_e32 v11, v50
	s_cmp_eq_u32 s2, 16
	s_cbranch_scc0 .LBB0_1736
	v_add_co_u32_e32 v16, vcc, s4, v2
	global_load_dwordx4 v[12:15], v[2:3], off
	s_nop 0
	v_addc_co_u32_e32 v17, vcc, -1, v3, vcc
	v_add_co_u32_e32 v62, vcc, s5, v2
	s_nop 0
	s_nop 0
	v_addc_co_u32_e32 v63, vcc, -1, v3, vcc
	v_add_co_u32_e32 v66, vcc, s11, v2
	s_nop 0
	s_nop 0
	v_addc_co_u32_e32 v67, vcc, 0, v3, vcc
	global_load_dwordx4 v[16:19], v[16:17], off
	s_nop 0
	global_load_dwordx4 v[62:65], v[62:63], off
	s_nop 0
	global_load_dwordx4 v[66:69], v[66:67], off
	v_lshl_add_u64 v[2:3], v[2:3], 0, s[20:21]
	v_add_co_u32_e32 v188, vcc, s4, v2
	global_load_dwordx4 v[184:187], v[2:3], off
	s_nop 0
	v_addc_co_u32_e32 v189, vcc, -1, v3, vcc
	v_add_co_u32_e32 v192, vcc, s5, v2
	s_nop 0
	s_nop 0
	v_addc_co_u32_e32 v193, vcc, -1, v3, vcc
	v_add_co_u32_e32 v196, vcc, s11, v2
	s_nop 0
	s_nop 0
	v_addc_co_u32_e32 v197, vcc, 0, v3, vcc
	global_load_dwordx4 v[188:191], v[188:189], off
	s_nop 0
	global_load_dwordx4 v[192:195], v[192:193], off
	s_nop 0
	global_load_dwordx4 v[196:199], v[196:197], off
	v_lshl_add_u64 v[2:3], v[2:3], 0, s[20:21]
	v_add_co_u32_e32 v204, vcc, s4, v2
	global_load_dwordx4 v[200:203], v[2:3], off
	s_nop 0
	v_addc_co_u32_e32 v205, vcc, -1, v3, vcc
	v_add_co_u32_e32 v208, vcc, s5, v2
	s_nop 0
	s_nop 0
	v_addc_co_u32_e32 v209, vcc, -1, v3, vcc
	v_add_co_u32_e32 v212, vcc, s11, v2
	s_nop 0
	s_nop 0
	v_addc_co_u32_e32 v213, vcc, 0, v3, vcc
	global_load_dwordx4 v[204:207], v[204:205], off
	s_nop 0
	global_load_dwordx4 v[208:211], v[208:209], off
	s_nop 0
	global_load_dwordx4 v[212:215], v[212:213], off
	v_lshl_add_u64 v[2:3], v[2:3], 0, s[20:21]
	v_add_co_u32_e32 v220, vcc, s4, v2
	global_load_dwordx4 v[216:219], v[2:3], off
	s_nop 0
	v_addc_co_u32_e32 v221, vcc, -1, v3, vcc
	v_add_co_u32_e32 v224, vcc, s5, v2
	s_nop 0
	s_nop 0
	v_addc_co_u32_e32 v225, vcc, -1, v3, vcc
	v_add_co_u32_e32 v228, vcc, s11, v2
	s_nop 0
	s_nop 0
	v_addc_co_u32_e32 v229, vcc, 0, v3, vcc
	global_load_dwordx4 v[220:223], v[220:221], off
	s_nop 0
	global_load_dwordx4 v[224:227], v[224:225], off
	s_nop 0
	global_load_dwordx4 v[228:231], v[228:229], off
	v_lshl_add_u64 v[2:3], v[2:3], 0, s[20:21]
	s_waitcnt vmcnt(12)
	v_pk_add_f32 v[54:55], v[54:55], v[14:15]
	v_pk_add_f32 v[56:57], v[56:57], v[12:13]
	v_pk_add_f32 v[10:11], v[10:11], v[18:19]
	v_pk_add_f32 v[8:9], v[8:9], v[16:17]
	v_pk_add_f32 v[60:61], v[60:61], v[64:65]
	v_pk_add_f32 v[58:59], v[58:59], v[62:63]
	v_pk_add_f32 v[52:53], v[52:53], v[68:69]
	v_pk_add_f32 v[50:51], v[50:51], v[66:67]
	s_waitcnt vmcnt(8)
	v_pk_add_f32 v[54:55], v[54:55], v[186:187]
	v_pk_add_f32 v[56:57], v[56:57], v[184:185]
	v_pk_add_f32 v[10:11], v[10:11], v[190:191]
	v_pk_add_f32 v[8:9], v[8:9], v[188:189]
	v_pk_add_f32 v[60:61], v[60:61], v[194:195]
	v_pk_add_f32 v[58:59], v[58:59], v[192:193]
	v_pk_add_f32 v[52:53], v[52:53], v[198:199]
	v_pk_add_f32 v[50:51], v[50:51], v[196:197]
	s_waitcnt vmcnt(4)
	v_pk_add_f32 v[54:55], v[54:55], v[202:203]
	v_pk_add_f32 v[56:57], v[56:57], v[200:201]
	v_pk_add_f32 v[10:11], v[10:11], v[206:207]
	v_pk_add_f32 v[8:9], v[8:9], v[204:205]
	v_pk_add_f32 v[60:61], v[60:61], v[210:211]
	v_pk_add_f32 v[58:59], v[58:59], v[208:209]
	v_pk_add_f32 v[52:53], v[52:53], v[214:215]
	v_pk_add_f32 v[50:51], v[50:51], v[212:213]
	s_waitcnt vmcnt(0)
	v_pk_add_f32 v[54:55], v[54:55], v[218:219]
	v_pk_add_f32 v[56:57], v[56:57], v[216:217]
	v_pk_add_f32 v[10:11], v[10:11], v[222:223]
	v_pk_add_f32 v[8:9], v[8:9], v[220:221]
	v_pk_add_f32 v[60:61], v[60:61], v[226:227]
	v_pk_add_f32 v[58:59], v[58:59], v[224:225]
	v_pk_add_f32 v[52:53], v[52:53], v[230:231]
	v_pk_add_f32 v[50:51], v[50:51], v[228:229]
	s_branch .Lfx_after_6

; template <class Epi> DI void gemm_fixup(int N, int K, const Epi& E, const float* part, int tid) {
;     ...
;                 for (int sl = 0; sl + 3 < S.S; sl += 4) { v0 += pp[(size_t)sl * 16384]; v1 += pp[(size_t)(sl + 1) * 16384]; v2 += pp[(size_t)(sl + 2) * 16384]; v3 += pp[(size_t)(sl + 3) * 16384]; }
;                 for (int sl = S.S & ~3; sl < S.S; ++sl) v0 += pp[(size_t)sl * 16384];
;                 a4[b][n] = (v0 + v1) + (v2 + v3); }
.Lfx_after_6:
	s_and_b64 vcc, exec, s[8:9]
	s_cbranch_vccz .LBB0_1739
	s_branch .LBB0_1741

; template <class Epi> DI void gemm_fixup(int N, int K, const Epi& E, const float* part, int tid) {
;     ...
;     for (int it = blockIdx.x; it < S.ntail * 8; it += gridDim.x) { const int j = it >> 3, ai = (it >> 2) & 1, m = it & 3; Unit u; S.map(S.nwhole * S.G + j, u);
;         f32x4 a4[2][2];
; #pragma unroll
;         for (int b = 0; b < 2; ++b)
; #pragma unroll
;             for (int n = 0; n < 2; ++n) { const f32x4* pp = (const f32x4*)part + ((size_t)(j * S.S) * 32 + (((ai * 2 + b) * 4 + m) * 2 + n)) * 512 + tid;
;                 f32x4 v0 = {0.f, 0.f, 0.f, 0.f}, v1 = v0, v2 = v0, v3 = v0;
;                 for (int sl = 0; sl + 3 < S.S; sl += 4) { v0 += pp[(size_t)sl * 16384]; v1 += pp[(size_t)(sl + 1) * 16384]; v2 += pp[(size_t)(sl + 2) * 16384]; v3 += pp[(size_t)(sl + 3) * 16384]; }
;                 for (int sl = S.S & ~3; sl < S.S; ++sl) v0 += pp[(size_t)sl * 16384];
;                 a4[b][n] = (v0 + v1) + (v2 + v3); }
.LBB0_1741:
	s_and_b64 vcc, exec, s[6:7]
	s_cbranch_vccnz .LBB0_1745
	s_add_u32 s34, s26, s19
	s_addc_u32 s35, s27, 0
	v_mov_b32_e32 v62, 0
	v_lshl_add_u64 v[2:3], v[28:29], 0, s[34:35]
	s_mov_b32 s29, 3
	v_mov_b32_e32 v63, v62
	v_mov_b32_e32 v64, v62
	v_mov_b32_e32 v65, v62
	v_mov_b32_e32 v68, v62
	v_mov_b32_e32 v69, v62
	v_mov_b32_e32 v66, v62
	v_mov_b32_e32 v67, v62
	v_mov_b32_e32 v70, v62
	v_mov_b32_e32 v71, v62
	v_mov_b32_e32 v72, v62
	v_mov_b32_e32 v73, v62
	v_mov_b32_e32 v12, v62
	v_mov_b32_e32 v13, v62
	v_mov_b32_e32 v14, v62
	v_mov_b32_e32 v15, v62
	s_cmp_eq_u32 s2, 16
	s_cbranch_scc0 .LBB0_1743
	v_add_co_u32_e32 v74, vcc, s4, v2
	global_load_dwordx4 v[16:19], v[2:3], off
	s_nop 0
	v_addc_co_u32_e32 v75, vcc, -1, v3, vcc
	v_add_co_u32_e32 v78, vcc, s5, v2
	s_nop 0
	s_nop 0
	v_addc_co_u32_e32 v79, vcc, -1, v3, vcc
	v_add_co_u32_e32 v82, vcc, s11, v2
	s_nop 0
	s_nop 0
	v_addc_co_u32_e32 v83, vcc, 0, v3, vcc
	global_load_dwordx4 v[74:77], v[74:75], off
	s_nop 0
	global_load_dwordx4 v[78:81], v[78:79], off
	s_nop 0
	global_load_dwordx4 v[82:85], v[82:83], off
	v_lshl_add_u64 v[2:3], v[2:3], 0, s[20:21]
	v_add_co_u32_e32 v188, vcc, s4, v2
	global_load_dwordx4 v[184:187], v[2:3], off
	s_nop 0
	v_addc_co_u32_e32 v189, vcc, -1, v3, vcc
	v_add_co_u32_e32 v192, vcc, s5, v2
	s_nop 0
	s_nop 0
	v_addc_co_u32_e32 v193, vcc, -1, v3, vcc
	v_add_co_u32_e32 v196, vcc, s11, v2
	s_nop 0
	s_nop 0
	v_addc_co_u32_e32 v197, vcc, 0, v3, vcc
	global_load_dwordx4 v[188:191], v[188:189], off
	s_nop 0
	global_load_dwordx4 v[192:195], v[192:193], off
	s_nop 0
	global_load_dwordx4 v[196:199], v[196:197], off
	v_lshl_add_u64 v[2:3], v[2:3], 0, s[20:21]
	v_add_co_u32_e32 v204, vcc, s4, v2
	global_load_dwordx4 v[200:203], v[2:3], off
	s_nop 0
	v_addc_co_u32_e32 v205, vcc, -1, v3, vcc
	v_add_co_u32_e32 v208, vcc, s5, v2
	s_nop 0
	s_nop 0
	v_addc_co_u32_e32 v209, vcc, -1, v3, vcc
	v_add_co_u32_e32 v212, vcc, s11, v2
	s_nop 0
	s_nop 0
	v_addc_co_u32_e32 v213, vcc, 0, v3, vcc
	global_load_dwordx4 v[204:207], v[204:205], off
	s_nop 0
	global_load_dwordx4 v[208:211], v[208:209], off
	s_nop 0
	global_load_dwordx4 v[212:215], v[212:213], off
	v_lshl_add_u64 v[2:3], v[2:3], 0, s[20:21]
	v_add_co_u32_e32 v220, vcc, s4, v2
	global_load_dwordx4 v[216:219], v[2:3], off
	s_nop 0
	v_addc_co_u32_e32 v221, vcc, -1, v3, vcc
	v_add_co_u32_e32 v224, vcc, s5, v2
	s_nop 0
	s_nop 0
	v_addc_co_u32_e32 v225, vcc, -1, v3, vcc
	v_add_co_u32_e32 v228, vcc, s11, v2
	s_nop 0
	s_nop 0
	v_addc_co_u32_e32 v229, vcc, 0, v3, vcc
	global_load_dwordx4 v[220:223], v[220:221], off
	s_nop 0
	global_load_dwordx4 v[224:227], v[224:225], off
	s_nop 0
	global_load_dwordx4 v[228:231], v[228:229], off
	v_lshl_add_u64 v[2:3], v[2:3], 0, s[20:21]
	s_waitcnt vmcnt(12)
	v_pk_add_f32 v[66:67], v[66:67], v[18:19]
	v_pk_add_f32 v[68:69], v[68:69], v[16:17]
	v_pk_add_f32 v[14:15], v[14:15], v[76:77]
	v_pk_add_f32 v[12:13], v[12:13], v[74:75]
	v_pk_add_f32 v[72:73], v[72:73], v[80:81]
	v_pk_add_f32 v[70:71], v[70:71], v[78:79]
	v_pk_add_f32 v[64:65], v[64:65], v[84:85]
	v_pk_add_f32 v[62:63], v[62:63], v[82:83]
	s_waitcnt vmcnt(8)
	v_pk_add_f32 v[66:67], v[66:67], v[186:187]
	v_pk_add_f32 v[68:69], v[68:69], v[184:185]
	v_pk_add_f32 v[14:15], v[14:15], v[190:191]
	v_pk_add_f32 v[12:13], v[12:13], v[188:189]
	v_pk_add_f32 v[72:73], v[72:73], v[194:195]
	v_pk_add_f32 v[70:71], v[70:71], v[192:193]
	v_pk_add_f32 v[64:65], v[64:65], v[198:199]
	v_pk_add_f32 v[62:63], v[62:63], v[196:197]
	s_waitcnt vmcnt(4)
	v_pk_add_f32 v[66:67], v[66:67], v[202:203]
	v_pk_add_f32 v[68:69], v[68:69], v[200:201]
	v_pk_add_f32 v[14:15], v[14:15], v[206:207]
	v_pk_add_f32 v[12:13], v[12:13], v[204:205]
	v_pk_add_f32 v[72:73], v[72:73], v[210:211]
	v_pk_add_f32 v[70:71], v[70:71], v[208:209]
	v_pk_add_f32 v[64:65], v[64:65], v[214:215]
	v_pk_add_f32 v[62:63], v[62:63], v[212:213]
	s_waitcnt vmcnt(0)
	v_pk_add_f32 v[66:67], v[66:67], v[218:219]
	v_pk_add_f32 v[68:69], v[68:69], v[216:217]
	v_pk_add_f32 v[14:15], v[14:15], v[222:223]
	v_pk_add_f32 v[12:13], v[12:13], v[220:221]
	v_pk_add_f32 v[72:73], v[72:73], v[226:227]
	v_pk_add_f32 v[70:71], v[70:71], v[224:225]
	v_pk_add_f32 v[64:65], v[64:65], v[230:231]
	v_pk_add_f32 v[62:63], v[62:63], v[228:229]
	s_branch .Lfx_after_5

; template <class Epi> DI void gemm_fixup(int N, int K, const Epi& E, const float* part, int tid) {
;     ...
;     for (int it = blockIdx.x; it < S.ntail * 8; it += gridDim.x) { const int j = it >> 3, ai = (it >> 2) & 1, m = it & 3; Unit u; S.map(S.nwhole * S.G + j, u);
;         f32x4 a4[2][2];
; #pragma unroll
;         for (int b = 0; b < 2; ++b)
; #pragma unroll
;             for (int n = 0; n < 2; ++n) { const f32x4* pp = (const f32x4*)part + ((size_t)(j * S.S) * 32 + (((ai * 2 + b) * 4 + m) * 2 + n)) * 512 + tid;
;                 f32x4 v0 = {0.f, 0.f, 0.f, 0.f}, v1 = v0, v2 = v0, v3 = v0;
;                 for (int sl = 0; sl + 3 < S.S; sl += 4) { v0 += pp[(size_t)sl * 16384]; v1 += pp[(size_t)(sl + 1) * 16384]; v2 += pp[(size_t)(sl + 2) * 16384]; v3 += pp[(size_t)(sl + 3) * 16384]; }
;                 for (int sl = S.S & ~3; sl < S.S; ++sl) v0 += pp[(size_t)sl * 16384];
;                 a4[b][n] = (v0 + v1) + (v2 + v3); }
.LBB0_1748:
	s_and_b64 vcc, exec, s[6:7]
	s_cbranch_vccnz .LBB0_1752
	s_add_u32 s34, s26, s19
	s_addc_u32 s35, s27, 0
	v_mov_b32_e32 v74, 0
	v_lshl_add_u64 v[2:3], v[32:33], 0, s[34:35]
	s_mov_b32 s29, 3
	v_mov_b32_e32 v75, v74
	v_mov_b32_e32 v76, v74
	v_mov_b32_e32 v77, v74
	v_mov_b32_e32 v80, v74
	v_mov_b32_e32 v81, v74
	v_mov_b32_e32 v78, v74
	v_mov_b32_e32 v79, v74
	v_mov_b32_e32 v82, v74
	v_mov_b32_e32 v83, v74
	v_mov_b32_e32 v84, v74
	v_mov_b32_e32 v85, v74
	v_mov_b32_e32 v16, v74
	v_mov_b32_e32 v17, v74
	v_mov_b32_e32 v18, v74
	v_mov_b32_e32 v19, v74
	s_cmp_eq_u32 s2, 16
	s_cbranch_scc0 .LBB0_1750
	v_add_co_u32_e32 v94, vcc, s4, v2
	global_load_dwordx4 v[90:93], v[2:3], off
	s_nop 0
	v_addc_co_u32_e32 v95, vcc, -1, v3, vcc
	v_add_co_u32_e32 v98, vcc, s5, v2
	s_nop 0
	s_nop 0
	v_addc_co_u32_e32 v99, vcc, -1, v3, vcc
	v_add_co_u32_e32 v102, vcc, s11, v2
	s_nop 0
	s_nop 0
	v_addc_co_u32_e32 v103, vcc, 0, v3, vcc
	global_load_dwordx4 v[94:97], v[94:95], off
	s_nop 0
	global_load_dwordx4 v[98:101], v[98:99], off
	s_nop 0
	global_load_dwordx4 v[102:105], v[102:103], off
	v_lshl_add_u64 v[2:3], v[2:3], 0, s[20:21]
	v_add_co_u32_e32 v188, vcc, s4, v2
	global_load_dwordx4 v[184:187], v[2:3], off
	s_nop 0
	v_addc_co_u32_e32 v189, vcc, -1, v3, vcc
	v_add_co_u32_e32 v192, vcc, s5, v2
	s_nop 0
	s_nop 0
	v_addc_co_u32_e32 v193, vcc, -1, v3, vcc
	v_add_co_u32_e32 v196, vcc, s11, v2
	s_nop 0
	s_nop 0
	v_addc_co_u32_e32 v197, vcc, 0, v3, vcc
	global_load_dwordx4 v[188:191], v[188:189], off
	s_nop 0
	global_load_dwordx4 v[192:195], v[192:193], off
	s_nop 0
	global_load_dwordx4 v[196:199], v[196:197], off
	v_lshl_add_u64 v[2:3], v[2:3], 0, s[20:21]
	v_add_co_u32_e32 v204, vcc, s4, v2
	global_load_dwordx4 v[200:203], v[2:3], off
	s_nop 0
	v_addc_co_u32_e32 v205, vcc, -1, v3, vcc
	v_add_co_u32_e32 v208, vcc, s5, v2
	s_nop 0
	s_nop 0
	v_addc_co_u32_e32 v209, vcc, -1, v3, vcc
	v_add_co_u32_e32 v212, vcc, s11, v2
	s_nop 0
	s_nop 0
	v_addc_co_u32_e32 v213, vcc, 0, v3, vcc
	global_load_dwordx4 v[204:207], v[204:205], off
	s_nop 0
	global_load_dwordx4 v[208:211], v[208:209], off
	s_nop 0
	global_load_dwordx4 v[212:215], v[212:213], off
	v_lshl_add_u64 v[2:3], v[2:3], 0, s[20:21]
	v_add_co_u32_e32 v220, vcc, s4, v2
	global_load_dwordx4 v[216:219], v[2:3], off
	s_nop 0
	v_addc_co_u32_e32 v221, vcc, -1, v3, vcc
	v_add_co_u32_e32 v224, vcc, s5, v2
	s_nop 0
	s_nop 0
	v_addc_co_u32_e32 v225, vcc, -1, v3, vcc
	v_add_co_u32_e32 v228, vcc, s11, v2
	s_nop 0
	s_nop 0
	v_addc_co_u32_e32 v229, vcc, 0, v3, vcc
	global_load_dwordx4 v[220:223], v[220:221], off
	s_nop 0
	global_load_dwordx4 v[224:227], v[224:225], off
	s_nop 0
	global_load_dwordx4 v[228:231], v[228:229], off
	v_lshl_add_u64 v[2:3], v[2:3], 0, s[20:21]
	s_waitcnt vmcnt(12)
	v_pk_add_f32 v[78:79], v[78:79], v[92:93]
	v_pk_add_f32 v[80:81], v[80:81], v[90:91]
	v_pk_add_f32 v[18:19], v[18:19], v[96:97]
	v_pk_add_f32 v[16:17], v[16:17], v[94:95]
	v_pk_add_f32 v[84:85], v[84:85], v[100:101]
	v_pk_add_f32 v[82:83], v[82:83], v[98:99]
	v_pk_add_f32 v[76:77], v[76:77], v[104:105]
	v_pk_add_f32 v[74:75], v[74:75], v[102:103]
	s_waitcnt vmcnt(8)
	v_pk_add_f32 v[78:79], v[78:79], v[186:187]
	v_pk_add_f32 v[80:81], v[80:81], v[184:185]
	v_pk_add_f32 v[18:19], v[18:19], v[190:191]
	v_pk_add_f32 v[16:17], v[16:17], v[188:189]
	v_pk_add_f32 v[84:85], v[84:85], v[194:195]
	v_pk_add_f32 v[82:83], v[82:83], v[192:193]
	v_pk_add_f32 v[76:77], v[76:77], v[198:199]
	v_pk_add_f32 v[74:75], v[74:75], v[196:197]
	s_waitcnt vmcnt(4)
	v_pk_add_f32 v[78:79], v[78:79], v[202:203]
	v_pk_add_f32 v[80:81], v[80:81], v[200:201]
	v_pk_add_f32 v[18:19], v[18:19], v[206:207]
	v_pk_add_f32 v[16:17], v[16:17], v[204:205]
	v_pk_add_f32 v[84:85], v[84:85], v[210:211]
	v_pk_add_f32 v[82:83], v[82:83], v[208:209]
	v_pk_add_f32 v[76:77], v[76:77], v[214:215]
	v_pk_add_f32 v[74:75], v[74:75], v[212:213]
	s_waitcnt vmcnt(0)
	v_pk_add_f32 v[78:79], v[78:79], v[218:219]
	v_pk_add_f32 v[80:81], v[80:81], v[216:217]
	v_pk_add_f32 v[18:19], v[18:19], v[222:223]
	v_pk_add_f32 v[16:17], v[16:17], v[220:221]
	v_pk_add_f32 v[84:85], v[84:85], v[226:227]
	v_pk_add_f32 v[82:83], v[82:83], v[224:225]
	v_pk_add_f32 v[76:77], v[76:77], v[230:231]
	v_pk_add_f32 v[74:75], v[74:75], v[228:229]
	s_branch .Lfx_after_4

; template <class Epi> DI void gemm_fixup(int N, int K, const Epi& E, const float* part, int tid) {
;     ...
;     for (int it = blockIdx.x; it < S.ntail * 8; it += gridDim.x) { const int j = it >> 3, ai = (it >> 2) & 1, m = it & 3; Unit u; S.map(S.nwhole * S.G + j, u);
;         f32x4 a4[2][2];
; #pragma unroll
;         for (int b = 0; b < 2; ++b)
; #pragma unroll
;             for (int n = 0; n < 2; ++n) { const f32x4* pp = (const f32x4*)part + ((size_t)(j * S.S) * 32 + (((ai * 2 + b) * 4 + m) * 2 + n)) * 512 + tid;
;                 f32x4 v0 = {0.f, 0.f, 0.f, 0.f}, v1 = v0, v2 = v0, v3 = v0;
;                 for (int sl = 0; sl + 3 < S.S; sl += 4) { v0 += pp[(size_t)sl * 16384]; v1 += pp[(size_t)(sl + 1) * 16384]; v2 += pp[(size_t)(sl + 2) * 16384]; v3 += pp[(size_t)(sl + 3) * 16384]; }
;                 for (int sl = S.S & ~3; sl < S.S; ++sl) v0 += pp[(size_t)sl * 16384];
;                 a4[b][n] = (v0 + v1) + (v2 + v3); }
.LBB0_2665:
	s_and_b32 s4, s20, 3
	s_lshl_b32 s5, s84, 15
	s_and_b32 s5, s5, 0x20000
	s_lshl_b32 s4, s4, 14
	s_or_b32 s22, s5, s4
	s_mul_i32 s4, s14, s16
	s_ashr_i32 s5, s4, 31
	s_and_b64 vcc, exec, s[2:3]
	s_lshl_b64 s[14:15], s[4:5], 18
	s_cbranch_vccnz .LBB0_2668
	s_add_u32 s4, s14, s22
	s_addc_u32 s5, s15, 0
	v_mov_b32_e32 v38, 0
	v_lshl_add_u64 v[2:3], v[20:21], 0, s[4:5]
	s_mov_b32 s4, 3
	v_mov_b32_e32 v39, v38
	v_mov_b32_e32 v40, v38
	v_mov_b32_e32 v41, v38
	v_mov_b32_e32 v44, v38
	v_mov_b32_e32 v45, v38
	v_mov_b32_e32 v42, v38
	v_mov_b32_e32 v43, v38
	v_mov_b32_e32 v46, v38
	v_mov_b32_e32 v47, v38
	v_mov_b32_e32 v48, v38
	v_mov_b32_e32 v49, v38
	s_waitcnt lgkmcnt(0)
	v_mov_b32_e32 v4, v38
	v_mov_b32_e32 v5, v38
	v_mov_b32_e32 v6, v38
	v_mov_b32_e32 v7, v38
	s_cmp_eq_u32 s16, 16
	s_cbranch_scc0 .LBB0_2667
	v_add_co_u32_e32 v54, vcc, s7, v2
	global_load_dwordx4 v[8:11], v[2:3], off
	s_nop 0
	v_addc_co_u32_e32 v55, vcc, -1, v3, vcc
	v_add_co_u32_e32 v56, vcc, s18, v2
	s_nop 0
	s_nop 0
	v_addc_co_u32_e32 v57, vcc, -1, v3, vcc
	v_add_co_u32_e32 v58, vcc, s19, v2
	s_nop 0
	s_nop 0
	v_addc_co_u32_e32 v59, vcc, 0, v3, vcc
	global_load_dwordx4 v[12:15], v[54:55], off
	global_load_dwordx4 v[16:19], v[56:57], off
	global_load_dwordx4 v[50:53], v[58:59], off
	v_lshl_add_u64 v[2:3], v[2:3], 0, s[10:11]
	v_add_co_u32_e32 v54, vcc, s7, v2
	global_load_dwordx4 v[184:187], v[2:3], off
	s_nop 0
	v_addc_co_u32_e32 v55, vcc, -1, v3, vcc
	v_add_co_u32_e32 v56, vcc, s18, v2
	s_nop 0
	s_nop 0
	v_addc_co_u32_e32 v57, vcc, -1, v3, vcc
	v_add_co_u32_e32 v58, vcc, s19, v2
	s_nop 0
	s_nop 0
	v_addc_co_u32_e32 v59, vcc, 0, v3, vcc
	global_load_dwordx4 v[188:191], v[54:55], off
	global_load_dwordx4 v[192:195], v[56:57], off
	global_load_dwordx4 v[196:199], v[58:59], off
	v_lshl_add_u64 v[2:3], v[2:3], 0, s[10:11]
	v_add_co_u32_e32 v54, vcc, s7, v2
	global_load_dwordx4 v[200:203], v[2:3], off
	s_nop 0
	v_addc_co_u32_e32 v55, vcc, -1, v3, vcc
	v_add_co_u32_e32 v56, vcc, s18, v2
	s_nop 0
	s_nop 0
	v_addc_co_u32_e32 v57, vcc, -1, v3, vcc
	v_add_co_u32_e32 v58, vcc, s19, v2
	s_nop 0
	s_nop 0
	v_addc_co_u32_e32 v59, vcc, 0, v3, vcc
	global_load_dwordx4 v[204:207], v[54:55], off
	global_load_dwordx4 v[208:211], v[56:57], off
	global_load_dwordx4 v[212:215], v[58:59], off
	v_lshl_add_u64 v[2:3], v[2:3], 0, s[10:11]
	v_add_co_u32_e32 v54, vcc, s7, v2
	global_load_dwordx4 v[216:219], v[2:3], off
	s_nop 0
	v_addc_co_u32_e32 v55, vcc, -1, v3, vcc
	v_add_co_u32_e32 v56, vcc, s18, v2
	s_nop 0
	s_nop 0
	v_addc_co_u32_e32 v57, vcc, -1, v3, vcc
	v_add_co_u32_e32 v58, vcc, s19, v2
	s_nop 0
	s_nop 0
	v_addc_co_u32_e32 v59, vcc, 0, v3, vcc
	global_load_dwordx4 v[220:223], v[54:55], off
	global_load_dwordx4 v[224:227], v[56:57], off
	global_load_dwordx4 v[228:231], v[58:59], off
	v_lshl_add_u64 v[2:3], v[2:3], 0, s[10:11]
	s_waitcnt vmcnt(12)
	v_pk_add_f32 v[42:43], v[42:43], v[10:11]
	v_pk_add_f32 v[44:45], v[44:45], v[8:9]
	v_pk_add_f32 v[6:7], v[6:7], v[14:15]
	v_pk_add_f32 v[4:5], v[4:5], v[12:13]
	v_pk_add_f32 v[48:49], v[48:49], v[18:19]
	v_pk_add_f32 v[46:47], v[46:47], v[16:17]
	v_pk_add_f32 v[40:41], v[40:41], v[52:53]
	v_pk_add_f32 v[38:39], v[38:39], v[50:51]
	s_waitcnt vmcnt(8)
	v_pk_add_f32 v[42:43], v[42:43], v[186:187]
	v_pk_add_f32 v[44:45], v[44:45], v[184:185]
	v_pk_add_f32 v[6:7], v[6:7], v[190:191]
	v_pk_add_f32 v[4:5], v[4:5], v[188:189]
	v_pk_add_f32 v[48:49], v[48:49], v[194:195]
	v_pk_add_f32 v[46:47], v[46:47], v[192:193]
	v_pk_add_f32 v[40:41], v[40:41], v[198:199]
	v_pk_add_f32 v[38:39], v[38:39], v[196:197]
	s_waitcnt vmcnt(4)
	v_pk_add_f32 v[42:43], v[42:43], v[202:203]
	v_pk_add_f32 v[44:45], v[44:45], v[200:201]
	v_pk_add_f32 v[6:7], v[6:7], v[206:207]
	v_pk_add_f32 v[4:5], v[4:5], v[204:205]
	v_pk_add_f32 v[48:49], v[48:49], v[210:211]
	v_pk_add_f32 v[46:47], v[46:47], v[208:209]
	v_pk_add_f32 v[40:41], v[40:41], v[214:215]
	v_pk_add_f32 v[38:39], v[38:39], v[212:213]
	s_waitcnt vmcnt(0)
	v_pk_add_f32 v[42:43], v[42:43], v[218:219]
	v_pk_add_f32 v[44:45], v[44:45], v[216:217]
	v_pk_add_f32 v[6:7], v[6:7], v[222:223]
	v_pk_add_f32 v[4:5], v[4:5], v[220:221]
	v_pk_add_f32 v[48:49], v[48:49], v[226:227]
	v_pk_add_f32 v[46:47], v[46:47], v[224:225]
	v_pk_add_f32 v[40:41], v[40:41], v[230:231]
	v_pk_add_f32 v[38:39], v[38:39], v[228:229]
	s_branch .Lfx_after_3
.LBB0_2667:
	v_add_co_u32_e32 v54, vcc, s7, v2
	global_load_dwordx4 v[8:11], v[2:3], off
	s_nop 0
	v_addc_co_u32_e32 v55, vcc, -1, v3, vcc
	v_add_co_u32_e32 v56, vcc, s18, v2
	s_add_i32 s4, s4, 4
	s_nop 0
	v_addc_co_u32_e32 v57, vcc, -1, v3, vcc
	v_add_co_u32_e32 v58, vcc, s19, v2
	s_cmp_ge_i32 s4, s16
	s_nop 0
	v_addc_co_u32_e32 v59, vcc, 0, v3, vcc
	global_load_dwordx4 v[12:15], v[54:55], off
	global_load_dwordx4 v[16:19], v[56:57], off
	global_load_dwordx4 v[50:53], v[58:59], off
	v_lshl_add_u64 v[2:3], v[2:3], 0, s[10:11]
	s_waitcnt vmcnt(3)
	v_pk_add_f32 v[42:43], v[42:43], v[10:11]
	v_pk_add_f32 v[44:45], v[44:45], v[8:9]
	s_waitcnt vmcnt(2)
	v_pk_add_f32 v[6:7], v[6:7], v[14:15]
	v_pk_add_f32 v[4:5], v[4:5], v[12:13]
	s_waitcnt vmcnt(1)
	v_pk_add_f32 v[48:49], v[48:49], v[18:19]
	v_pk_add_f32 v[46:47], v[46:47], v[16:17]
	s_waitcnt vmcnt(0)
	v_pk_add_f32 v[40:41], v[40:41], v[52:53]
	v_pk_add_f32 v[38:39], v[38:39], v[50:51]
	s_cbranch_scc0 .LBB0_2667
.Lfx_after_3:
	s_branch .LBB0_2669
.LBB0_2668:
	v_mov_b32_e32 v2, v0
	v_mov_b32_e32 v3, v0
	v_mov_b32_e32 v1, v0
	v_mov_b32_e32 v41, 0
	s_waitcnt lgkmcnt(0)
	v_mov_b64_e32 v[6:7], v[2:3]
	v_mov_b32_e32 v40, v41
	v_mov_b32_e32 v39, v41
	v_mov_b32_e32 v38, v41
	v_mov_b32_e32 v43, v41
	v_mov_b32_e32 v42, v41
	v_mov_b32_e32 v45, v41
	v_mov_b32_e32 v44, v41
	v_mov_b32_e32 v49, v41
	v_mov_b32_e32 v48, v41
	v_mov_b32_e32 v47, v41
	v_mov_b32_e32 v46, v41
	v_mov_b64_e32 v[4:5], v[0:1]

; template <class Epi> DI void gemm_fixup(int N, int K, const Epi& E, const float* part, int tid) {
;     ...
;     for (int it = blockIdx.x; it < S.ntail * 8; it += gridDim.x) { const int j = it >> 3, ai = (it >> 2) & 1, m = it & 3; Unit u; S.map(S.nwhole * S.G + j, u);
;         f32x4 a4[2][2];
; #pragma unroll
;         for (int b = 0; b < 2; ++b)
; #pragma unroll
;             for (int n = 0; n < 2; ++n) { const f32x4* pp = (const f32x4*)part + ((size_t)(j * S.S) * 32 + (((ai * 2 + b) * 4 + m) * 2 + n)) * 512 + tid;
;                 f32x4 v0 = {0.f, 0.f, 0.f, 0.f}, v1 = v0, v2 = v0, v3 = v0;
;                 for (int sl = 0; sl + 3 < S.S; sl += 4) { v0 += pp[(size_t)sl * 16384]; v1 += pp[(size_t)(sl + 1) * 16384]; v2 += pp[(size_t)(sl + 2) * 16384]; v3 += pp[(size_t)(sl + 3) * 16384]; }
;                 for (int sl = S.S & ~3; sl < S.S; ++sl) v0 += pp[(size_t)sl * 16384];
;                 a4[b][n] = (v0 + v1) + (v2 + v3); }
.LBB0_2672:
	s_and_b64 vcc, exec, s[2:3]
	s_cbranch_vccnz .LBB0_2676
	s_add_u32 s26, s14, s22
	s_addc_u32 s27, s15, 0
	v_mov_b32_e32 v50, 0
	v_lshl_add_u64 v[2:3], v[24:25], 0, s[26:27]
	s_mov_b32 s25, 3
	v_mov_b32_e32 v51, v50
	v_mov_b32_e32 v52, v50
	v_mov_b32_e32 v53, v50
	v_mov_b32_e32 v56, v50
	v_mov_b32_e32 v57, v50
	v_mov_b32_e32 v54, v50
	v_mov_b32_e32 v55, v50
	v_mov_b32_e32 v58, v50
	v_mov_b32_e32 v59, v50
	v_mov_b32_e32 v60, v50
	v_mov_b32_e32 v61, v50
	v_mov_b32_e32 v8, v50
	v_mov_b32_e32 v9, v50
	v_mov_b32_e32 v10, v50
	v_mov_b32_e32 v11, v50
	s_cmp_eq_u32 s16, 16
	s_cbranch_scc0 .LBB0_2674
	v_add_co_u32_e32 v16, vcc, s7, v2
	global_load_dwordx4 v[12:15], v[2:3], off
	s_nop 0
	v_addc_co_u32_e32 v17, vcc, -1, v3, vcc
	v_add_co_u32_e32 v70, vcc, s18, v2
	s_nop 0
	s_nop 0
	v_addc_co_u32_e32 v71, vcc, -1, v3, vcc
	v_add_co_u32_e32 v72, vcc, s19, v2
	s_nop 0
	s_nop 0
	v_addc_co_u32_e32 v73, vcc, 0, v3, vcc
	global_load_dwordx4 v[16:19], v[16:17], off
	s_nop 0
	global_load_dwordx4 v[62:65], v[70:71], off
	global_load_dwordx4 v[66:69], v[72:73], off
	v_lshl_add_u64 v[2:3], v[2:3], 0, s[10:11]
	v_add_co_u32_e32 v188, vcc, s7, v2
	global_load_dwordx4 v[184:187], v[2:3], off
	s_nop 0
	v_addc_co_u32_e32 v189, vcc, -1, v3, vcc
	v_add_co_u32_e32 v70, vcc, s18, v2
	s_nop 0
	s_nop 0
	v_addc_co_u32_e32 v71, vcc, -1, v3, vcc
	v_add_co_u32_e32 v72, vcc, s19, v2
	s_nop 0
	s_nop 0
	v_addc_co_u32_e32 v73, vcc, 0, v3, vcc
	global_load_dwordx4 v[188:191], v[188:189], off
	s_nop 0
	global_load_dwordx4 v[192:195], v[70:71], off
	global_load_dwordx4 v[196:199], v[72:73], off
	v_lshl_add_u64 v[2:3], v[2:3], 0, s[10:11]
	v_add_co_u32_e32 v204, vcc, s7, v2
	global_load_dwordx4 v[200:203], v[2:3], off
	s_nop 0
	v_addc_co_u32_e32 v205, vcc, -1, v3, vcc
	v_add_co_u32_e32 v70, vcc, s18, v2
	s_nop 0
	s_nop 0
	v_addc_co_u32_e32 v71, vcc, -1, v3, vcc
	v_add_co_u32_e32 v72, vcc, s19, v2
	s_nop 0
	s_nop 0
	v_addc_co_u32_e32 v73, vcc, 0, v3, vcc
	global_load_dwordx4 v[204:207], v[204:205], off
	s_nop 0
	global_load_dwordx4 v[208:211], v[70:71], off
	global_load_dwordx4 v[212:215], v[72:73], off
	v_lshl_add_u64 v[2:3], v[2:3], 0, s[10:11]
	v_add_co_u32_e32 v220, vcc, s7, v2
	global_load_dwordx4 v[216:219], v[2:3], off
	s_nop 0
	v_addc_co_u32_e32 v221, vcc, -1, v3, vcc
	v_add_co_u32_e32 v70, vcc, s18, v2
	s_nop 0
	s_nop 0
	v_addc_co_u32_e32 v71, vcc, -1, v3, vcc
	v_add_co_u32_e32 v72, vcc, s19, v2
	s_nop 0
	s_nop 0
	v_addc_co_u32_e32 v73, vcc, 0, v3, vcc
	global_load_dwordx4 v[220:223], v[220:221], off
	s_nop 0
	global_load_dwordx4 v[224:227], v[70:71], off
	global_load_dwordx4 v[228:231], v[72:73], off
	v_lshl_add_u64 v[2:3], v[2:3], 0, s[10:11]
	s_waitcnt vmcnt(12)
	v_pk_add_f32 v[54:55], v[54:55], v[14:15]
	v_pk_add_f32 v[56:57], v[56:57], v[12:13]
	v_pk_add_f32 v[10:11], v[10:11], v[18:19]
	v_pk_add_f32 v[8:9], v[8:9], v[16:17]
	v_pk_add_f32 v[60:61], v[60:61], v[64:65]
	v_pk_add_f32 v[58:59], v[58:59], v[62:63]
	v_pk_add_f32 v[52:53], v[52:53], v[68:69]
	v_pk_add_f32 v[50:51], v[50:51], v[66:67]
	s_waitcnt vmcnt(8)
	v_pk_add_f32 v[54:55], v[54:55], v[186:187]
	v_pk_add_f32 v[56:57], v[56:57], v[184:185]
	v_pk_add_f32 v[10:11], v[10:11], v[190:191]
	v_pk_add_f32 v[8:9], v[8:9], v[188:189]
	v_pk_add_f32 v[60:61], v[60:61], v[194:195]
	v_pk_add_f32 v[58:59], v[58:59], v[192:193]
	v_pk_add_f32 v[52:53], v[52:53], v[198:199]
	v_pk_add_f32 v[50:51], v[50:51], v[196:197]
	s_waitcnt vmcnt(4)
	v_pk_add_f32 v[54:55], v[54:55], v[202:203]
	v_pk_add_f32 v[56:57], v[56:57], v[200:201]
	v_pk_add_f32 v[10:11], v[10:11], v[206:207]
	v_pk_add_f32 v[8:9], v[8:9], v[204:205]
	v_pk_add_f32 v[60:61], v[60:61], v[210:211]
	v_pk_add_f32 v[58:59], v[58:59], v[208:209]
	v_pk_add_f32 v[52:53], v[52:53], v[214:215]
	v_pk_add_f32 v[50:51], v[50:51], v[212:213]
	s_waitcnt vmcnt(0)
	v_pk_add_f32 v[54:55], v[54:55], v[218:219]
	v_pk_add_f32 v[56:57], v[56:57], v[216:217]
	v_pk_add_f32 v[10:11], v[10:11], v[222:223]
	v_pk_add_f32 v[8:9], v[8:9], v[220:221]
	v_pk_add_f32 v[60:61], v[60:61], v[226:227]
	v_pk_add_f32 v[58:59], v[58:59], v[224:225]
	v_pk_add_f32 v[52:53], v[52:53], v[230:231]
	v_pk_add_f32 v[50:51], v[50:51], v[228:229]
	s_branch .Lfx_after_2

; template <class Epi> DI void gemm_fixup(int N, int K, const Epi& E, const float* part, int tid) {
;     ...
;                 for (int sl = 0; sl + 3 < S.S; sl += 4) { v0 += pp[(size_t)sl * 16384]; v1 += pp[(size_t)(sl + 1) * 16384]; v2 += pp[(size_t)(sl + 2) * 16384]; v3 += pp[(size_t)(sl + 3) * 16384]; }
;                 for (int sl = S.S & ~3; sl < S.S; ++sl) v0 += pp[(size_t)sl * 16384];
;                 a4[b][n] = (v0 + v1) + (v2 + v3); }
.Lfx_after_2:
	s_and_b64 vcc, exec, s[4:5]
	s_cbranch_vccz .LBB0_2677
	s_branch .LBB0_2679

; template <class Epi> DI void gemm_fixup(int N, int K, const Epi& E, const float* part, int tid) {
;     ...
;     for (int it = blockIdx.x; it < S.ntail * 8; it += gridDim.x) { const int j = it >> 3, ai = (it >> 2) & 1, m = it & 3; Unit u; S.map(S.nwhole * S.G + j, u);
;         f32x4 a4[2][2];
; #pragma unroll
;         for (int b = 0; b < 2; ++b)
; #pragma unroll
;             for (int n = 0; n < 2; ++n) { const f32x4* pp = (const f32x4*)part + ((size_t)(j * S.S) * 32 + (((ai * 2 + b) * 4 + m) * 2 + n)) * 512 + tid;
;                 f32x4 v0 = {0.f, 0.f, 0.f, 0.f}, v1 = v0, v2 = v0, v3 = v0;
;                 for (int sl = 0; sl + 3 < S.S; sl += 4) { v0 += pp[(size_t)sl * 16384]; v1 += pp[(size_t)(sl + 1) * 16384]; v2 += pp[(size_t)(sl + 2) * 16384]; v3 += pp[(size_t)(sl + 3) * 16384]; }
;                 for (int sl = S.S & ~3; sl < S.S; ++sl) v0 += pp[(size_t)sl * 16384];
;                 a4[b][n] = (v0 + v1) + (v2 + v3); }
.LBB0_2679:
	s_and_b64 vcc, exec, s[2:3]
	s_cbranch_vccnz .LBB0_2683
	s_add_u32 s26, s14, s22
	s_addc_u32 s27, s15, 0
	v_mov_b32_e32 v62, 0
	v_lshl_add_u64 v[2:3], v[28:29], 0, s[26:27]
	s_mov_b32 s25, 3
	v_mov_b32_e32 v63, v62
	v_mov_b32_e32 v64, v62
	v_mov_b32_e32 v65, v62
	v_mov_b32_e32 v68, v62
	v_mov_b32_e32 v69, v62
	v_mov_b32_e32 v66, v62
	v_mov_b32_e32 v67, v62
	v_mov_b32_e32 v70, v62
	v_mov_b32_e32 v71, v62
	v_mov_b32_e32 v72, v62
	v_mov_b32_e32 v73, v62
	v_mov_b32_e32 v12, v62
	v_mov_b32_e32 v13, v62
	v_mov_b32_e32 v14, v62
	v_mov_b32_e32 v15, v62
	s_cmp_eq_u32 s16, 16
	s_cbranch_scc0 .LBB0_2681
	v_add_co_u32_e32 v74, vcc, s7, v2
	global_load_dwordx4 v[16:19], v[2:3], off
	s_nop 0
	v_addc_co_u32_e32 v75, vcc, -1, v3, vcc
	v_add_co_u32_e32 v90, vcc, s18, v2
	s_nop 0
	s_nop 0
	v_addc_co_u32_e32 v91, vcc, -1, v3, vcc
	v_add_co_u32_e32 v92, vcc, s19, v2
	s_nop 0
	s_nop 0
	v_addc_co_u32_e32 v93, vcc, 0, v3, vcc
	global_load_dwordx4 v[74:77], v[74:75], off
	s_nop 0
	global_load_dwordx4 v[78:81], v[90:91], off
	global_load_dwordx4 v[82:85], v[92:93], off
	v_lshl_add_u64 v[2:3], v[2:3], 0, s[10:11]
	v_add_co_u32_e32 v188, vcc, s7, v2
	global_load_dwordx4 v[184:187], v[2:3], off
	s_nop 0
	v_addc_co_u32_e32 v189, vcc, -1, v3, vcc
	v_add_co_u32_e32 v90, vcc, s18, v2
	s_nop 0
	s_nop 0
	v_addc_co_u32_e32 v91, vcc, -1, v3, vcc
	v_add_co_u32_e32 v92, vcc, s19, v2
	s_nop 0
	s_nop 0
	v_addc_co_u32_e32 v93, vcc, 0, v3, vcc
	global_load_dwordx4 v[188:191], v[188:189], off
	s_nop 0
	global_load_dwordx4 v[192:195], v[90:91], off
	global_load_dwordx4 v[196:199], v[92:93], off
	v_lshl_add_u64 v[2:3], v[2:3], 0, s[10:11]
	v_add_co_u32_e32 v204, vcc, s7, v2
	global_load_dwordx4 v[200:203], v[2:3], off
	s_nop 0
	v_addc_co_u32_e32 v205, vcc, -1, v3, vcc
	v_add_co_u32_e32 v90, vcc, s18, v2
	s_nop 0
	s_nop 0
	v_addc_co_u32_e32 v91, vcc, -1, v3, vcc
	v_add_co_u32_e32 v92, vcc, s19, v2
	s_nop 0
	s_nop 0
	v_addc_co_u32_e32 v93, vcc, 0, v3, vcc
	global_load_dwordx4 v[204:207], v[204:205], off
	s_nop 0
	global_load_dwordx4 v[208:211], v[90:91], off
	global_load_dwordx4 v[212:215], v[92:93], off
	v_lshl_add_u64 v[2:3], v[2:3], 0, s[10:11]
	v_add_co_u32_e32 v220, vcc, s7, v2
	global_load_dwordx4 v[216:219], v[2:3], off
	s_nop 0
	v_addc_co_u32_e32 v221, vcc, -1, v3, vcc
	v_add_co_u32_e32 v90, vcc, s18, v2
	s_nop 0
	s_nop 0
	v_addc_co_u32_e32 v91, vcc, -1, v3, vcc
	v_add_co_u32_e32 v92, vcc, s19, v2
	s_nop 0
	s_nop 0
	v_addc_co_u32_e32 v93, vcc, 0, v3, vcc
	global_load_dwordx4 v[220:223], v[220:221], off
	s_nop 0
	global_load_dwordx4 v[224:227], v[90:91], off
	global_load_dwordx4 v[228:231], v[92:93], off
	v_lshl_add_u64 v[2:3], v[2:3], 0, s[10:11]
	s_waitcnt vmcnt(12)
	v_pk_add_f32 v[66:67], v[66:67], v[18:19]
	v_pk_add_f32 v[68:69], v[68:69], v[16:17]
	v_pk_add_f32 v[14:15], v[14:15], v[76:77]
	v_pk_add_f32 v[12:13], v[12:13], v[74:75]
	v_pk_add_f32 v[72:73], v[72:73], v[80:81]
	v_pk_add_f32 v[70:71], v[70:71], v[78:79]
	v_pk_add_f32 v[64:65], v[64:65], v[84:85]
	v_pk_add_f32 v[62:63], v[62:63], v[82:83]
	s_waitcnt vmcnt(8)
	v_pk_add_f32 v[66:67], v[66:67], v[186:187]
	v_pk_add_f32 v[68:69], v[68:69], v[184:185]
	v_pk_add_f32 v[14:15], v[14:15], v[190:191]
	v_pk_add_f32 v[12:13], v[12:13], v[188:189]
	v_pk_add_f32 v[72:73], v[72:73], v[194:195]
	v_pk_add_f32 v[70:71], v[70:71], v[192:193]
	v_pk_add_f32 v[64:65], v[64:65], v[198:199]
	v_pk_add_f32 v[62:63], v[62:63], v[196:197]
	s_waitcnt vmcnt(4)
	v_pk_add_f32 v[66:67], v[66:67], v[202:203]
	v_pk_add_f32 v[68:69], v[68:69], v[200:201]
	v_pk_add_f32 v[14:15], v[14:15], v[206:207]
	v_pk_add_f32 v[12:13], v[12:13], v[204:205]
	v_pk_add_f32 v[72:73], v[72:73], v[210:211]
	v_pk_add_f32 v[70:71], v[70:71], v[208:209]
	v_pk_add_f32 v[64:65], v[64:65], v[214:215]
	v_pk_add_f32 v[62:63], v[62:63], v[212:213]
	s_waitcnt vmcnt(0)
	v_pk_add_f32 v[66:67], v[66:67], v[218:219]
	v_pk_add_f32 v[68:69], v[68:69], v[216:217]
	v_pk_add_f32 v[14:15], v[14:15], v[222:223]
	v_pk_add_f32 v[12:13], v[12:13], v[220:221]
	v_pk_add_f32 v[72:73], v[72:73], v[226:227]
	v_pk_add_f32 v[70:71], v[70:71], v[224:225]
	v_pk_add_f32 v[64:65], v[64:65], v[230:231]
	v_pk_add_f32 v[62:63], v[62:63], v[228:229]
	s_branch .Lfx_after_1

; template <class Epi> DI void gemm_fixup(int N, int K, const Epi& E, const float* part, int tid) {
;     ...
;     for (int it = blockIdx.x; it < S.ntail * 8; it += gridDim.x) { const int j = it >> 3, ai = (it >> 2) & 1, m = it & 3; Unit u; S.map(S.nwhole * S.G + j, u);
;         f32x4 a4[2][2];
; #pragma unroll
;         for (int b = 0; b < 2; ++b)
; #pragma unroll
;             for (int n = 0; n < 2; ++n) { const f32x4* pp = (const f32x4*)part + ((size_t)(j * S.S) * 32 + (((ai * 2 + b) * 4 + m) * 2 + n)) * 512 + tid;
;                 f32x4 v0 = {0.f, 0.f, 0.f, 0.f}, v1 = v0, v2 = v0, v3 = v0;
;                 for (int sl = 0; sl + 3 < S.S; sl += 4) { v0 += pp[(size_t)sl * 16384]; v1 += pp[(size_t)(sl + 1) * 16384]; v2 += pp[(size_t)(sl + 2) * 16384]; v3 += pp[(size_t)(sl + 3) * 16384]; }
;                 for (int sl = S.S & ~3; sl < S.S; ++sl) v0 += pp[(size_t)sl * 16384];
;                 a4[b][n] = (v0 + v1) + (v2 + v3); }
.LBB0_2686:
	s_and_b64 vcc, exec, s[2:3]
	s_cbranch_vccnz .LBB0_2690
	s_add_u32 s26, s14, s22
	s_addc_u32 s27, s15, 0
	v_mov_b32_e32 v74, 0
	v_lshl_add_u64 v[2:3], v[32:33], 0, s[26:27]
	s_mov_b32 s25, 3
	v_mov_b32_e32 v75, v74
	v_mov_b32_e32 v76, v74
	v_mov_b32_e32 v77, v74
	v_mov_b32_e32 v80, v74
	v_mov_b32_e32 v81, v74
	v_mov_b32_e32 v78, v74
	v_mov_b32_e32 v79, v74
	v_mov_b32_e32 v82, v74
	v_mov_b32_e32 v83, v74
	v_mov_b32_e32 v84, v74
	v_mov_b32_e32 v85, v74
	v_mov_b32_e32 v16, v74
	v_mov_b32_e32 v17, v74
	v_mov_b32_e32 v18, v74
	v_mov_b32_e32 v19, v74
	s_cmp_eq_u32 s16, 16
	s_cbranch_scc0 .LBB0_2688
	v_add_co_u32_e32 v94, vcc, s7, v2
	global_load_dwordx4 v[90:93], v[2:3], off
	s_nop 0
	v_addc_co_u32_e32 v95, vcc, -1, v3, vcc
	v_add_co_u32_e32 v106, vcc, s18, v2
	s_nop 0
	s_nop 0
	v_addc_co_u32_e32 v107, vcc, -1, v3, vcc
	v_add_co_u32_e32 v108, vcc, s19, v2
	s_nop 0
	s_nop 0
	v_addc_co_u32_e32 v109, vcc, 0, v3, vcc
	global_load_dwordx4 v[94:97], v[94:95], off
	s_nop 0
	global_load_dwordx4 v[98:101], v[106:107], off
	global_load_dwordx4 v[102:105], v[108:109], off
	v_lshl_add_u64 v[2:3], v[2:3], 0, s[10:11]
	v_add_co_u32_e32 v188, vcc, s7, v2
	global_load_dwordx4 v[184:187], v[2:3], off
	s_nop 0
	v_addc_co_u32_e32 v189, vcc, -1, v3, vcc
	v_add_co_u32_e32 v106, vcc, s18, v2
	s_nop 0
	s_nop 0
	v_addc_co_u32_e32 v107, vcc, -1, v3, vcc
	v_add_co_u32_e32 v108, vcc, s19, v2
	s_nop 0
	s_nop 0
	v_addc_co_u32_e32 v109, vcc, 0, v3, vcc
	global_load_dwordx4 v[188:191], v[188:189], off
	s_nop 0
	global_load_dwordx4 v[192:195], v[106:107], off
	global_load_dwordx4 v[196:199], v[108:109], off
	v_lshl_add_u64 v[2:3], v[2:3], 0, s[10:11]
	v_add_co_u32_e32 v204, vcc, s7, v2
	global_load_dwordx4 v[200:203], v[2:3], off
	s_nop 0
	v_addc_co_u32_e32 v205, vcc, -1, v3, vcc
	v_add_co_u32_e32 v106, vcc, s18, v2
	s_nop 0
	s_nop 0
	v_addc_co_u32_e32 v107, vcc, -1, v3, vcc
	v_add_co_u32_e32 v108, vcc, s19, v2
	s_nop 0
	s_nop 0
	v_addc_co_u32_e32 v109, vcc, 0, v3, vcc
	global_load_dwordx4 v[204:207], v[204:205], off
	s_nop 0
	global_load_dwordx4 v[208:211], v[106:107], off
	global_load_dwordx4 v[212:215], v[108:109], off
	v_lshl_add_u64 v[2:3], v[2:3], 0, s[10:11]
	v_add_co_u32_e32 v220, vcc, s7, v2
	global_load_dwordx4 v[216:219], v[2:3], off
	s_nop 0
	v_addc_co_u32_e32 v221, vcc, -1, v3, vcc
	v_add_co_u32_e32 v106, vcc, s18, v2
	s_nop 0
	s_nop 0
	v_addc_co_u32_e32 v107, vcc, -1, v3, vcc
	v_add_co_u32_e32 v108, vcc, s19, v2
	s_nop 0
	s_nop 0
	v_addc_co_u32_e32 v109, vcc, 0, v3, vcc
	global_load_dwordx4 v[220:223], v[220:221], off
	s_nop 0
	global_load_dwordx4 v[224:227], v[106:107], off
	global_load_dwordx4 v[228:231], v[108:109], off
	v_lshl_add_u64 v[2:3], v[2:3], 0, s[10:11]
	s_waitcnt vmcnt(12)
	v_pk_add_f32 v[78:79], v[78:79], v[92:93]
	v_pk_add_f32 v[80:81], v[80:81], v[90:91]
	v_pk_add_f32 v[18:19], v[18:19], v[96:97]
	v_pk_add_f32 v[16:17], v[16:17], v[94:95]
	v_pk_add_f32 v[84:85], v[84:85], v[100:101]
	v_pk_add_f32 v[82:83], v[82:83], v[98:99]
	v_pk_add_f32 v[76:77], v[76:77], v[104:105]
	v_pk_add_f32 v[74:75], v[74:75], v[102:103]
	s_waitcnt vmcnt(8)
	v_pk_add_f32 v[78:79], v[78:79], v[186:187]
	v_pk_add_f32 v[80:81], v[80:81], v[184:185]
	v_pk_add_f32 v[18:19], v[18:19], v[190:191]
	v_pk_add_f32 v[16:17], v[16:17], v[188:189]
	v_pk_add_f32 v[84:85], v[84:85], v[194:195]
	v_pk_add_f32 v[82:83], v[82:83], v[192:193]
	v_pk_add_f32 v[76:77], v[76:77], v[198:199]
	v_pk_add_f32 v[74:75], v[74:75], v[196:197]
	s_waitcnt vmcnt(4)
	v_pk_add_f32 v[78:79], v[78:79], v[202:203]
	v_pk_add_f32 v[80:81], v[80:81], v[200:201]
	v_pk_add_f32 v[18:19], v[18:19], v[206:207]
	v_pk_add_f32 v[16:17], v[16:17], v[204:205]
	v_pk_add_f32 v[84:85], v[84:85], v[210:211]
	v_pk_add_f32 v[82:83], v[82:83], v[208:209]
	v_pk_add_f32 v[76:77], v[76:77], v[214:215]
	v_pk_add_f32 v[74:75], v[74:75], v[212:213]
	s_waitcnt vmcnt(0)
	v_pk_add_f32 v[78:79], v[78:79], v[218:219]
	v_pk_add_f32 v[80:81], v[80:81], v[216:217]
	v_pk_add_f32 v[18:19], v[18:19], v[222:223]
	v_pk_add_f32 v[16:17], v[16:17], v[220:221]
	v_pk_add_f32 v[84:85], v[84:85], v[226:227]
	v_pk_add_f32 v[82:83], v[82:83], v[224:225]
	v_pk_add_f32 v[76:77], v[76:77], v[230:231]
	v_pk_add_f32 v[74:75], v[74:75], v[228:229]
	s_branch .Lfx_after_0
